# v15 + NSA pre-loop: compressed-attention QK fragment reads issued up front (counted lgkmcnt), lane^32 max/sum exchanges via v_permlane32_swap
# baseline (speedup 1.0000x reference)
; #define LAS __attribute__((address_space(3)))
; DI void nsa_item(KA a, LAS unsigned char* lds, const int it) {
;     const int tid = tid_(), lane = tid & 63, w = tid >> 6, r = lane & 31, hf = lane >> 5;
;     const int qb = 31 - (it >> 5), bg = it & 31, b = bg >> 1, g = bg & 1, hh = w >> 1, head = g * 4 + hh, tql = 32 * (w & 1) + r;
;     unsigned char* ws = a->ws; const bf16* H = (const bf16*)(ws + WS_H); bf16* act = (bf16*)(ws + WS_ACT);
;     const size_t tokrow = (size_t)b * SEQ + 64 * qb + tql;
;     LAS bf16* Kt = (LAS bf16*)(lds + NSA_KT); LAS bf16* VT = (LAS bf16*)(lds + NSA_VT); LAS float* IMP = (LAS float*)(lds + NSA_IMP); LAS float* IMPT = (LAS float*)(lds + NSA_IMPT);
;     LAS unsigned* SELM = (LAS unsigned*)(lds + NSA_SELM); LAS int* LIST = (LAS int*)(lds + NSA_LIST); LAS int* NLIST = (LAS int*)(lds + NSA_NLIST);
;     bf16x8 bq[4];
; #pragma unroll
;     for (int s = 0; s < 4; ++s) bq[s] = *(const bf16x8*)(H + tokrow * HP + C_NQ + head * 64 + 16 * s + 8 * hf);
;     const float g0 = sigmoidf_(ldbf(H + tokrow * HP + C_NG + head * 3 + 0)), g1 = sigmoidf_(ldbf(H + tokrow * HP + C_NG + head * 3 + 1)), g2 = sigmoidf_(ldbf(H + tokrow * HP + C_NG + head * 3 + 2));
;     v4u kreg; v2u vr0, vr1;
;     const int skey = tid >> 3, sch = tid & 7, sdg = tid & 15, skp = tid >> 4;
;     ...
;     NSA_LOAD(0);
;     { const bf16* kc = (const bf16*)(ws + WS_KCMP) + (size_t)bg * 128 * 64; const bf16* vc = (const bf16*)(ws + WS_VCMP) + (size_t)bg * 128 * 64;
; #pragma unroll
;       for (int i = 0; i < 2; ++i) { const int idx = tid + NTHR * i; const int c = idx >> 3, ch = idx & 7; *(LAS v4u*)(Kt + c * PA + 8 * ch) = *(const v4u*)(kc + c * 64 + 8 * ch);
;           const int dg = idx & 15, kp = idx >> 4; const v2u v0 = *(const v2u*)(vc + (2 * kp) * 64 + 4 * dg), v1 = *(const v2u*)(vc + (2 * kp + 1) * 64 + 4 * dg);
;           LAS unsigned* d0 = (LAS unsigned*)(VT + (4 * dg) * PV + vpos(2 * kp));
;           d0[0] = (v0.x & 0xffffu) | (v1.x << 16); d0[PV / 2] = (v0.x >> 16) | (v1.x & 0xffff0000u); d0[PV] = (v0.y & 0xffffu) | (v1.y << 16); d0[3 * PV / 2] = (v0.y >> 16) | (v1.y & 0xffff0000u); } }
;     __syncthreads();
;     ...
;         __syncthreads();
;         if (tid_() == 0) *(LAS int*)(lds + NSA_ITEM) = (int)atomicAdd(ctr, 1u);
;         __syncthreads();
;         const int it = *(LAS int*)(lds + NSA_ITEM);
;         if (it >= 1024) break;
.LBB0_607:
	s_or_b64 exec, exec, s[0:1]
	v_readlane_b32 s0, v254, 6
	s_waitcnt lgkmcnt(0)
	s_barrier
	v_mov_b32_e32 v0, s0
	ds_read_b32 v0, v0
	s_movk_i32 s0, 0x3ff
	s_waitcnt lgkmcnt(0)
	v_cmp_lt_i32_e32 vcc, s0, v0
	v_readfirstlane_b32 s2, v0
	s_mov_b64 s[0:1], -1
	s_cbranch_vccnz .LBB0_602
	s_ashr_i32 s40, s2, 5
	s_sub_i32 s3, 31, s40
	s_lshl_b32 s0, s2, 10
	v_writelane_b32 v254, s3, 47
	v_mov_b32_e32 v87, v232
	s_and_b32 s1, s2, 31
	s_and_b32 s41, s2, 1
	s_and_b32 s6, s0, 0x7800
	s_lshl_b32 s0, s3, 6
	v_readlane_b32 s2, v254, 39
	v_readlane_b32 s3, v254, 40
	v_ashrrev_i32_e32 v132, 3, v87
	v_add_u32_e32 v0, s6, v132
	s_waitcnt vmcnt(5)
	v_mov_b64_e32 v[8:9], s[2:3]
	s_movk_i32 s5, 0x1c00
	s_lshl_b32 s90, s41, 7
	v_mad_i64_i32 v[0:1], s[2:3], v0, s5, v[8:9]
	v_and_b32_e32 v133, -2, v132
	s_waitcnt vmcnt(4)
	v_lshl_add_u64 v[10:11], v[0:1], 0, s[90:91]
	v_add_u32_e32 v0, s6, v133
	v_writelane_b32 v254, s6, 48
	v_mad_i64_i32 v[0:1], s[2:3], v0, s5, v[8:9]
	s_or_b32 s90, s90, 0x1760
	s_add_i32 s4, s6, s0
	v_lshl_add_u64 v[4:5], v[0:1], 0, s[90:91]
	v_lshlrev_b32_e32 v0, 2, v87
	s_lshl_b32 s1, s1, 14
	v_readlane_b32 s2, v254, 41
	v_and_b32_e32 v136, 60, v0
	s_add_u32 s2, s2, s1
	v_readlane_b32 s3, v254, 42
	v_lshlrev_b32_e32 v0, 4, v87
	s_addc_u32 s3, s3, 0
	s_waitcnt vmcnt(3)
	v_and_b32_e32 v12, 0x70, v0
	v_mov_b32_e32 v13, v193
	s_waitcnt vmcnt(2)
	v_lshlrev_b32_e32 v14, 6, v132
	v_lshl_add_u64 v[6:7], s[2:3], 0, v[12:13]
	v_ashrrev_i32_e32 v15, 31, v14
	v_lshl_add_u64 v[0:1], v[14:15], 1, v[6:7]
	v_readlane_b32 s2, v254, 43
	v_lshlrev_b32_e32 v88, 1, v136
	v_mov_b32_e32 v89, v193
	global_load_dwordx4 v[0:3], v[0:1], off
	s_add_u32 s2, s2, s1
	v_readlane_b32 s1, v254, 46
	s_addc_u32 s3, s1, 0
	v_and_b32_e32 v18, 0xffffff80, v14
	v_or_b32_e32 v14, 64, v14
	v_lshl_add_u64 v[20:21], v[4:5], 0, v[88:89]
	s_movk_i32 s1, 0x1000
	v_lshl_add_u64 v[16:17], s[2:3], 0, v[88:89]
	v_ashrrev_i32_e32 v19, 31, v18
	v_ashrrev_i32_e32 v15, 31, v14
	v_add_co_u32_e32 v4, vcc, s1, v20
	v_lshl_add_u64 v[18:19], v[18:19], 1, v[16:17]
	v_lshl_add_u64 v[14:15], v[14:15], 1, v[16:17]
	v_addc_co_u32_e32 v5, vcc, 0, v21, vcc
	global_load_dwordx2 v[18:19], v[18:19], off
	s_nop 0
	global_load_dwordx2 v[14:15], v[14:15], off
	v_ashrrev_i32_e32 v143, 6, v87
	global_load_dwordx2 v[94:95], v[4:5], off offset:3072
	v_add_u32_e32 v4, 0x200, v87
	v_ashrrev_i32_e32 v13, 3, v4
	v_lshlrev_b32_e32 v22, 6, v13
	v_ashrrev_i32_e32 v23, 31, v22
	v_lshl_add_u64 v[4:5], v[22:23], 1, v[6:7]
	global_load_dwordx4 v[4:7], v[4:5], off
	v_and_b32_e32 v24, 0xffffff80, v22
	v_ashrrev_i32_e32 v25, 31, v24
	v_or_b32_e32 v22, 64, v22
	v_lshl_add_u64 v[24:25], v[24:25], 1, v[16:17]
	v_ashrrev_i32_e32 v23, 31, v22
	global_load_dwordx2 v[24:25], v[24:25], off
	v_lshl_add_u64 v[16:17], v[22:23], 1, v[16:17]
	global_load_dwordx2 v[16:17], v[16:17], off
	v_and_b32_e32 v89, 31, v87
	v_ashrrev_i32_e32 v146, 7, v87
	v_lshlrev_b32_e32 v22, 5, v143
	v_lshl_add_u32 v28, s41, 2, v146
	v_and_or_b32 v135, v22, 32, v89
	v_or_b32_e32 v86, s4, v135
	v_lshlrev_b32_e32 v84, 6, v28
	v_bfe_u32 v137, v87, 5, 1
	v_mad_u64_u32 v[8:9], s[2:3], v86, s5, v[8:9]
	v_ashrrev_i32_e32 v85, 31, v84
	v_lshl_add_u64 v[22:23], v[84:85], 1, v[8:9]
	v_lshlrev_b32_e32 v90, 4, v137
	v_mov_b32_e32 v91, v193
	v_lshl_add_u64 v[22:23], v[22:23], 0, v[90:91]
	s_mov_b64 s[2:3], 0x1060
	v_lshl_add_u64 v[26:27], v[22:23], 0, s[2:3]
	v_add_co_u32_e32 v22, vcc, s1, v22
	s_mov_b64 s[2:3], 0x1a60
	s_nop 0
	v_addc_co_u32_e32 v23, vcc, 0, v23, vcc
	global_load_dwordx4 v[64:67], v[26:27], off offset:32
	global_load_dwordx4 v[68:71], v[26:27], off offset:64
	global_load_dwordx4 v[72:75], v[22:23], off offset:96
	global_load_dwordx4 v[76:79], v[26:27], off offset:96
	v_lshl_add_u32 v22, v28, 1, v28
	v_ashrrev_i32_e32 v23, 31, v22
	v_lshl_add_u64 v[8:9], v[22:23], 1, v[8:9]
	v_and_b32_e32 v141, 7, v87
	v_lshl_add_u64 v[22:23], v[8:9], 0, s[2:3]
	v_add_co_u32_e32 v8, vcc, s1, v8
	v_lshlrev_b32_e32 v192, 4, v141
	s_nop 0
	v_addc_co_u32_e32 v9, vcc, 0, v9, vcc
	v_lshl_add_u64 v[10:11], v[10:11], 0, v[192:193]
	v_add_co_u32_e32 v10, vcc, s1, v10
	s_movk_i32 s4, 0x110
	s_nop 0
	v_addc_co_u32_e32 v11, vcc, 0, v11, vcc
	global_load_dword v142, v[8:9], off offset:2656
	global_load_dwordx4 v[80:83], v[10:11], off offset:1632
	global_load_dwordx2 v[96:97], v[20:21], off
	global_load_ushort v91, v[22:23], off offset:4
	v_add_u32_e32 v8, 0, v12
	v_mad_u32_u24 v9, v136, s4, 0
	v_mad_u64_u32 v[10:11], s[2:3], v132, s75, v[8:9]
	v_and_b32_e32 v140, -14, v132
	s_mov_b32 s1, 0xffff0000
	s_waitcnt vmcnt(14)
	ds_write_b128 v10, v[0:3]
	v_lshrrev_b32_e32 v0, 1, v132
	v_and_b32_e32 v138, 4, v0
	v_lshlrev_b32_e32 v0, 1, v132
	v_and_b32_e32 v139, 8, v0
	v_lshl_add_u32 v0, v140, 1, v9
	v_lshlrev_b32_e32 v1, 1, v138
	v_lshlrev_b32_e32 v2, 1, v139
	v_add3_u32 v0, v0, v1, v2
	v_add_u32_e32 v0, 0x4800, v0
	v_add_u32_e32 v112, 0, v90
	v_mad_u32_u24 v92, v89, s75, v112
	v_lshlrev_b32_e32 v93, 6, v137
	s_cmp_gt_i32 s40, 15
	s_waitcnt vmcnt(13)
	v_and_b32_e32 v1, 0xffff, v18
	v_lshrrev_b32_e32 v2, 16, v18
	s_waitcnt vmcnt(12)
	v_lshl_or_b32 v1, v14, 16, v1
	v_and_or_b32 v2, v14, s1, v2
	ds_write2_b32 v0, v1, v2 offset1:68
	v_and_b32_e32 v1, 0xffff, v19
	v_lshrrev_b32_e32 v2, 16, v19
	v_lshl_or_b32 v1, v15, 16, v1
	v_and_or_b32 v2, v15, s1, v2
	ds_write2_b32 v0, v1, v2 offset0:136 offset1:204
	v_mad_u64_u32 v[0:1], s[2:3], v13, s75, v[8:9]
	s_waitcnt vmcnt(10)
	ds_write_b128 v0, v[4:7]
	v_lshlrev_b32_e32 v0, 1, v13
	v_and_b32_e32 v0, 0xffffffe4, v0
	v_lshlrev_b32_e32 v2, 2, v13
	v_add_u32_e32 v0, v9, v0
	v_and_b32_e32 v1, 8, v13
	v_and_b32_e32 v2, 16, v2
	v_add3_u32 v0, v0, v1, v2
	s_waitcnt vmcnt(9)
	v_and_b32_e32 v1, 0xffff, v24
	v_lshrrev_b32_e32 v2, 16, v24
	s_waitcnt vmcnt(8)
	v_lshl_or_b32 v1, v16, 16, v1
	v_and_or_b32 v2, v16, s1, v2
	v_add_u32_e32 v0, 0x4800, v0
	ds_write2_b32 v0, v1, v2 offset1:68
	v_and_b32_e32 v1, 0xffff, v25
	v_lshrrev_b32_e32 v2, 16, v25
	v_lshl_or_b32 v1, v17, 16, v1
	v_and_or_b32 v2, v17, s1, v2
	ds_write2_b32 v0, v1, v2 offset0:136 offset1:204
	s_waitcnt lgkmcnt(0)
	s_barrier
; #define LAS __attribute__((address_space(3)))
; DI f32x16 mma32(bf16x8 a, bf16x8 b, f32x16 c) { return __builtin_amdgcn_mfma_f32_32x32x16_bf16(a, b, c, 0, 0, 0); }
; DI int crow(int i, int hf) { return (i & 3) + 8 * (i >> 2) + 4 * hf; }
; DI void nsa_item(KA a, LAS unsigned char* lds, const int it) {
;     ...
;         f32x16 st[4] = {ZERO16, ZERO16, ZERO16, ZERO16};
; #pragma unroll
;         for (int k4 = 0; k4 < 4; ++k4)
; #pragma unroll
;             for (int s = 0; s < 4; ++s) { const bf16x8 af = *(const LAS bf16x8*)(Kt + (32 * k4 + r) * PA + 16 * s + 8 * hf); st[k4] = mma32(af, bq[s], st[k4]); }
;         const int tq = 64 * qb + tql; float mx = -INFINITY;
; #pragma unroll
;         for (int k4 = 0; k4 < 4; ++k4)
; #pragma unroll
;             for (int i = 0; i < 16; ++i) { const int c = 32 * k4 + crow(i, hf); const bool ok = (16 * c + 31 <= tq); st[k4][i] = ok ? st[k4][i] : -INFINITY; mx = fmaxf(mx, st[k4][i]); }
	ds_read_b128 v[170:173], v92
	ds_read_b128 v[174:177], v92 offset:32
	ds_read_b128 v[178:181], v92 offset:64
	ds_read_b128 v[182:185], v92 offset:96
	ds_read_b128 v[186:189], v92 offset:4608
	ds_read_b128 v[206:209], v92 offset:4640
	ds_read_b128 v[210:213], v92 offset:4672
	ds_read_b128 v[214:217], v92 offset:4704
	ds_read_b128 v[218:221], v92 offset:9216
	ds_read_b128 v[222:225], v92 offset:9248
	ds_read_b128 v[226:229], v92 offset:9280
	ds_read_b128 v[98:101], v92 offset:9312
	ds_read_b128 v[0:3], v92 offset:13824
	s_waitcnt vmcnt(5) lgkmcnt(12)
	v_mfma_f32_32x32x16_bf16 v[48:63], v[170:173], v[72:75], 0
	ds_read_b128 v[170:173], v92 offset:13856
	s_waitcnt lgkmcnt(12)
	v_mfma_f32_32x32x16_bf16 v[48:63], v[174:177], v[64:67], v[48:63]
	ds_read_b128 v[174:177], v92 offset:13888
	s_waitcnt lgkmcnt(12)
	v_mfma_f32_32x32x16_bf16 v[48:63], v[178:181], v[68:71], v[48:63]
	ds_read_b128 v[178:181], v92 offset:13920
	s_waitcnt vmcnt(4) lgkmcnt(12)
	v_mfma_f32_32x32x16_bf16 v[48:63], v[182:185], v[76:79], v[48:63]
	s_waitcnt lgkmcnt(11)
	v_mfma_f32_32x32x16_bf16 v[32:47], v[186:189], v[72:75], 0
	s_waitcnt lgkmcnt(10)
	v_mfma_f32_32x32x16_bf16 v[32:47], v[206:209], v[64:67], v[32:47]
	s_waitcnt lgkmcnt(9)
	v_mfma_f32_32x32x16_bf16 v[32:47], v[210:213], v[68:71], v[32:47]
	s_waitcnt lgkmcnt(8)
	v_mfma_f32_32x32x16_bf16 v[32:47], v[214:217], v[76:79], v[32:47]
	s_waitcnt lgkmcnt(7)
	v_mfma_f32_32x32x16_bf16 v[16:31], v[218:221], v[72:75], 0
	s_waitcnt lgkmcnt(6)
	v_mfma_f32_32x32x16_bf16 v[16:31], v[222:225], v[64:67], v[16:31]
	s_waitcnt lgkmcnt(5)
	v_mfma_f32_32x32x16_bf16 v[16:31], v[226:229], v[68:71], v[16:31]
	s_waitcnt lgkmcnt(4)
	v_mfma_f32_32x32x16_bf16 v[16:31], v[98:101], v[76:79], v[16:31]
	s_waitcnt lgkmcnt(3)
	v_mfma_f32_32x32x16_bf16 v[0:15], v[0:3], v[72:75], 0
	s_waitcnt lgkmcnt(2)
	v_mfma_f32_32x32x16_bf16 v[0:15], v[170:173], v[64:67], v[0:15]
	s_waitcnt lgkmcnt(1)
	v_mfma_f32_32x32x16_bf16 v[0:15], v[174:177], v[68:71], v[0:15]
	s_waitcnt lgkmcnt(0)
	v_or_b32_e32 v92, s0, v135
	s_mov_b32 s0, 0xff800000
	v_mfma_f32_32x32x16_bf16 v[0:15], v[178:181], v[76:79], v[0:15]
	v_or_b32_e32 v98, 31, v93
	v_cmp_le_u32_e32 vcc, v98, v92
	v_or_b32_e32 v98, 47, v93
	v_or_b32_e32 v99, 63, v93
	v_cndmask_b32_e32 v48, v240, v48, vcc
	v_cmp_le_u32_e32 vcc, v98, v92
	s_nop 1
	v_cndmask_b32_e32 v49, v240, v49, vcc
	v_cmp_le_u32_e32 vcc, v99, v92
	v_add_u32_e32 v99, 0x4f, v93
	v_max3_f32 v98, v48, s0, v49
	v_cndmask_b32_e32 v50, v240, v50, vcc
	v_cmp_le_u32_e32 vcc, v99, v92
	v_or_b32_e32 v99, 0x9f, v93
	s_nop 0
	v_cndmask_b32_e32 v51, v240, v51, vcc
	v_cmp_le_u32_e32 vcc, v99, v92
	v_or_b32_e32 v99, 0xaf, v93
	v_max3_f32 v98, v98, v50, v51
	v_cndmask_b32_e32 v52, v240, v52, vcc
	v_cmp_le_u32_e32 vcc, v99, v92
	v_or_b32_e32 v99, 0xbf, v93
	s_nop 0
	v_cndmask_b32_e32 v53, v240, v53, vcc
	v_cmp_le_u32_e32 vcc, v99, v92
	v_add_u32_e32 v99, 0xcf, v93
	v_max3_f32 v98, v98, v52, v53
	v_cndmask_b32_e32 v54, v240, v54, vcc
	v_cmp_le_u32_e32 vcc, v99, v92
	v_or_b32_e32 v99, 0x11f, v93
	s_nop 0
	v_cndmask_b32_e32 v55, v240, v55, vcc
	v_cmp_le_u32_e32 vcc, v99, v92
	v_or_b32_e32 v99, 0x12f, v93
	v_max3_f32 v98, v98, v54, v55
	v_cndmask_b32_e32 v56, v240, v56, vcc
	v_cmp_le_u32_e32 vcc, v99, v92
	v_or_b32_e32 v99, 0x13f, v93
	s_nop 0
	v_cndmask_b32_e32 v57, v240, v57, vcc
	v_cmp_le_u32_e32 vcc, v99, v92
	v_add_u32_e32 v99, 0x14f, v93
	v_max3_f32 v98, v98, v56, v57
	v_cndmask_b32_e32 v58, v240, v58, vcc
	v_cmp_le_u32_e32 vcc, v99, v92
	v_or_b32_e32 v99, 0x19f, v93
	s_nop 0
	v_cndmask_b32_e32 v59, v240, v59, vcc
	v_cmp_le_u32_e32 vcc, v99, v92
	v_or_b32_e32 v99, 0x1af, v93
	v_max3_f32 v98, v98, v58, v59
	v_cndmask_b32_e32 v60, v240, v60, vcc
	v_cmp_le_u32_e32 vcc, v99, v92
	v_or_b32_e32 v99, 0x1bf, v93
	s_nop 0
	v_cndmask_b32_e32 v61, v240, v61, vcc
	v_cmp_le_u32_e32 vcc, v99, v92
	v_add_u32_e32 v99, 0x1cf, v93
	v_max3_f32 v98, v98, v60, v61
	v_cndmask_b32_e32 v62, v240, v62, vcc
	v_cmp_le_u32_e32 vcc, v99, v92
	v_or_b32_e32 v99, 0x21f, v93
	s_nop 0
	v_cndmask_b32_e32 v63, v240, v63, vcc
	v_cmp_le_u32_e32 vcc, v99, v92
	v_or_b32_e32 v99, 0x22f, v93
	v_max3_f32 v98, v98, v62, v63
	v_cndmask_b32_e32 v32, v240, v32, vcc
	v_cmp_le_u32_e32 vcc, v99, v92
	v_or_b32_e32 v99, 0x23f, v93
	s_nop 0
	v_cndmask_b32_e32 v33, v240, v33, vcc
	v_cmp_le_u32_e32 vcc, v99, v92
	v_add_u32_e32 v99, 0x24f, v93
	v_max3_f32 v98, v98, v32, v33
	v_cndmask_b32_e32 v34, v240, v34, vcc
	v_cmp_le_u32_e32 vcc, v99, v92
	v_or_b32_e32 v99, 0x29f, v93
	s_nop 0
	v_cndmask_b32_e32 v35, v240, v35, vcc
	v_cmp_le_u32_e32 vcc, v99, v92
	v_or_b32_e32 v99, 0x2af, v93
	v_max3_f32 v98, v98, v34, v35
	v_cndmask_b32_e32 v36, v240, v36, vcc
	v_cmp_le_u32_e32 vcc, v99, v92
	v_or_b32_e32 v99, 0x2bf, v93
	s_nop 0
	v_cndmask_b32_e32 v37, v240, v37, vcc
	v_cmp_le_u32_e32 vcc, v99, v92
	v_add_u32_e32 v99, 0x2cf, v93
	v_max3_f32 v98, v98, v36, v37
	v_cndmask_b32_e32 v38, v240, v38, vcc
	v_cmp_le_u32_e32 vcc, v99, v92
	v_or_b32_e32 v99, 0x31f, v93
	s_nop 0
	v_cndmask_b32_e32 v39, v240, v39, vcc
	v_cmp_le_u32_e32 vcc, v99, v92
	v_or_b32_e32 v99, 0x32f, v93
	v_max3_f32 v98, v98, v38, v39
	v_cndmask_b32_e32 v40, v240, v40, vcc
	v_cmp_le_u32_e32 vcc, v99, v92
	v_or_b32_e32 v99, 0x33f, v93
	s_nop 0
	v_cndmask_b32_e32 v41, v240, v41, vcc
	v_cmp_le_u32_e32 vcc, v99, v92
	v_add_u32_e32 v99, 0x34f, v93
	v_max3_f32 v98, v98, v40, v41
	v_cndmask_b32_e32 v42, v240, v42, vcc
	v_cmp_le_u32_e32 vcc, v99, v92
	v_or_b32_e32 v99, 0x39f, v93
	s_nop 0
	v_cndmask_b32_e32 v43, v240, v43, vcc
	v_cmp_le_u32_e32 vcc, v99, v92
	v_or_b32_e32 v99, 0x3af, v93
	v_max3_f32 v98, v98, v42, v43
	v_cndmask_b32_e32 v44, v240, v44, vcc
; DI int crow(int i, int hf) { return (i & 3) + 8 * (i >> 2) + 4 * hf; }
; DI void nsa_item(KA a, LAS unsigned char* lds, const int it) {
;     ...
;         const int tq = 64 * qb + tql; float mx = -INFINITY;
; #pragma unroll
;         for (int k4 = 0; k4 < 4; ++k4)
; #pragma unroll
;             for (int i = 0; i < 16; ++i) { const int c = 32 * k4 + crow(i, hf); const bool ok = (16 * c + 31 <= tq); st[k4][i] = ok ? st[k4][i] : -INFINITY; mx = fmaxf(mx, st[k4][i]); }
;         mx = fmaxf(mx, __shfl_xor(mx, 32)); const float mref = (mx == -INFINITY) ? 0.f : mx; float ls = 0.f;
	v_cmp_le_u32_e32 vcc, v99, v92
	v_or_b32_e32 v99, 0x3bf, v93
	s_nop 0
	v_cndmask_b32_e32 v45, v240, v45, vcc
	v_cmp_le_u32_e32 vcc, v99, v92
	v_add_u32_e32 v99, 0x3cf, v93
	v_max3_f32 v98, v98, v44, v45
	v_cndmask_b32_e32 v46, v240, v46, vcc
	v_cmp_le_u32_e32 vcc, v99, v92
	v_or_b32_e32 v99, 0x41f, v93
	s_nop 0
	v_cndmask_b32_e32 v47, v240, v47, vcc
	v_cmp_le_u32_e32 vcc, v99, v92
	v_or_b32_e32 v99, 0x42f, v93
	v_max3_f32 v98, v98, v46, v47
	v_cndmask_b32_e32 v16, v240, v16, vcc
	v_cmp_le_u32_e32 vcc, v99, v92
	v_or_b32_e32 v99, 0x43f, v93
	s_nop 0
	v_cndmask_b32_e32 v17, v240, v17, vcc
	v_cmp_le_u32_e32 vcc, v99, v92
	v_add_u32_e32 v99, 0x44f, v93
	v_max3_f32 v98, v98, v16, v17
	v_cndmask_b32_e32 v18, v240, v18, vcc
	v_cmp_le_u32_e32 vcc, v99, v92
	v_or_b32_e32 v99, 0x49f, v93
	s_nop 0
	v_cndmask_b32_e32 v19, v240, v19, vcc
	v_cmp_le_u32_e32 vcc, v99, v92
	v_or_b32_e32 v99, 0x4af, v93
	v_max3_f32 v98, v98, v18, v19
	v_cndmask_b32_e32 v20, v240, v20, vcc
	v_cmp_le_u32_e32 vcc, v99, v92
	v_or_b32_e32 v99, 0x4bf, v93
	s_nop 0
	v_cndmask_b32_e32 v21, v240, v21, vcc
	v_cmp_le_u32_e32 vcc, v99, v92
	v_add_u32_e32 v99, 0x4cf, v93
	v_max3_f32 v98, v98, v20, v21
	v_cndmask_b32_e32 v22, v240, v22, vcc
	v_cmp_le_u32_e32 vcc, v99, v92
	v_or_b32_e32 v99, 0x51f, v93
	s_nop 0
	v_cndmask_b32_e32 v23, v240, v23, vcc
	v_cmp_le_u32_e32 vcc, v99, v92
	v_or_b32_e32 v99, 0x52f, v93
	v_max3_f32 v98, v98, v22, v23
	v_cndmask_b32_e32 v24, v240, v24, vcc
	v_cmp_le_u32_e32 vcc, v99, v92
	v_or_b32_e32 v99, 0x53f, v93
	s_nop 0
	v_cndmask_b32_e32 v25, v240, v25, vcc
	v_cmp_le_u32_e32 vcc, v99, v92
	v_add_u32_e32 v99, 0x54f, v93
	v_max3_f32 v98, v98, v24, v25
	v_cndmask_b32_e32 v26, v240, v26, vcc
	v_cmp_le_u32_e32 vcc, v99, v92
	v_or_b32_e32 v99, 0x59f, v93
	s_nop 0
	v_cndmask_b32_e32 v27, v240, v27, vcc
	v_cmp_le_u32_e32 vcc, v99, v92
	v_or_b32_e32 v99, 0x5af, v93
	v_max3_f32 v98, v98, v26, v27
	v_cndmask_b32_e32 v28, v240, v28, vcc
	v_cmp_le_u32_e32 vcc, v99, v92
	v_or_b32_e32 v99, 0x5bf, v93
	s_nop 0
	v_cndmask_b32_e32 v29, v240, v29, vcc
	v_cmp_le_u32_e32 vcc, v99, v92
	v_add_u32_e32 v99, 0x5cf, v93
	v_max3_f32 v98, v98, v28, v29
	v_cndmask_b32_e32 v30, v240, v30, vcc
	v_cmp_le_u32_e32 vcc, v99, v92
	v_or_b32_e32 v99, 0x61f, v93
	s_nop 0
	v_cndmask_b32_e32 v31, v240, v31, vcc
	v_cmp_le_u32_e32 vcc, v99, v92
	v_max3_f32 v98, v98, v30, v31
	s_nop 0
	v_cndmask_b32_e32 v113, v240, v0, vcc
	v_or_b32_e32 v0, 0x62f, v93
	v_cmp_le_u32_e32 vcc, v0, v92
	s_nop 1
	v_cndmask_b32_e32 v116, v240, v1, vcc
	v_or_b32_e32 v1, 0x63f, v93
	v_cmp_le_u32_e32 vcc, v1, v92
	v_add_u32_e32 v1, 0x64f, v93
	v_max3_f32 v0, v98, v113, v116
	v_cndmask_b32_e32 v117, v240, v2, vcc
	v_cmp_le_u32_e32 vcc, v1, v92
	v_or_b32_e32 v1, 0x69f, v93
	v_and_b32_e32 v2, 64, v238
	v_cndmask_b32_e32 v130, v240, v3, vcc
	v_cmp_le_u32_e32 vcc, v1, v92
	v_or_b32_e32 v1, 0x6af, v93
	v_max3_f32 v0, v0, v117, v130
	v_cndmask_b32_e32 v131, v240, v4, vcc
	v_cmp_le_u32_e32 vcc, v1, v92
	v_or_b32_e32 v1, 0x6bf, v93
	v_add_u32_e32 v144, 64, v2
	v_cndmask_b32_e32 v145, v240, v5, vcc
	v_cmp_le_u32_e32 vcc, v1, v92
	v_add_u32_e32 v1, 0x6cf, v93
	v_max3_f32 v0, v0, v131, v145
	v_cndmask_b32_e32 v147, v240, v6, vcc
	v_cmp_le_u32_e32 vcc, v1, v92
	v_or_b32_e32 v1, 0x71f, v93
	s_nop 0
	v_cndmask_b32_e32 v148, v240, v7, vcc
	v_cmp_le_u32_e32 vcc, v1, v92
	v_or_b32_e32 v1, 0x72f, v93
	v_max3_f32 v0, v0, v147, v148
	v_cndmask_b32_e32 v149, v240, v8, vcc
	v_cmp_le_u32_e32 vcc, v1, v92
	v_or_b32_e32 v1, 0x73f, v93
	s_nop 0
	v_cndmask_b32_e32 v150, v240, v9, vcc
	v_cmp_le_u32_e32 vcc, v1, v92
	v_add_u32_e32 v1, 0x74f, v93
	v_max3_f32 v0, v0, v149, v150
	v_cndmask_b32_e32 v10, v240, v10, vcc
	v_cmp_le_u32_e32 vcc, v1, v92
	v_or_b32_e32 v1, 0x79f, v93
	s_nop 0
	v_cndmask_b32_e32 v11, v240, v11, vcc
	v_cmp_le_u32_e32 vcc, v1, v92
	v_or_b32_e32 v1, 0x7af, v93
	v_max3_f32 v0, v0, v10, v11
	v_cndmask_b32_e32 v12, v240, v12, vcc
	v_cmp_le_u32_e32 vcc, v1, v92
	v_or_b32_e32 v1, 0x7bf, v93
	s_nop 0
	v_cndmask_b32_e32 v13, v240, v13, vcc
	v_cmp_le_u32_e32 vcc, v1, v92
	v_add_u32_e32 v1, 0x7cf, v93
	v_max3_f32 v0, v0, v12, v13
	v_cndmask_b32_e32 v14, v240, v14, vcc
	v_cmp_le_u32_e32 vcc, v1, v92
	v_xor_b32_e32 v1, 32, v238
	s_nop 0
	v_cndmask_b32_e32 v15, v240, v15, vcc
	v_cmp_lt_i32_e32 vcc, v1, v144
	v_max3_f32 v0, v0, v14, v15
	s_nop 0
	v_cndmask_b32_e32 v1, v238, v1, vcc
	v_lshlrev_b32_e32 v134, 2, v1
	v_mov_b32_e32 v1, v0
	s_waitcnt lgkmcnt(0)
; DI void nsa_item(KA a, LAS unsigned char* lds, const int it) {
;     ...
;         mx = fmaxf(mx, __shfl_xor(mx, 32)); const float mref = (mx == -INFINITY) ? 0.f : mx; float ls = 0.f;
; #pragma unroll
;         for (int k4 = 0; k4 < 4; ++k4)
; #pragma unroll
;             for (int i = 0; i < 16; ++i) { const float p = __builtin_amdgcn_exp2f(st[k4][i] - mref); st[k4][i] = p; ls += p; }
	s_nop 1
	v_permlane32_swap_b32_e32 v1, v0
	v_max_f32_e32 v0, v0, v1
	v_cmp_neq_f32_e32 vcc, s0, v0
	s_nop 1
	v_cndmask_b32_e32 v151, 0, v0, vcc
	v_sub_f32_e32 v0, v48, v151
	v_exp_f32_e32 v0, v0
	v_sub_f32_e32 v1, v49, v151
	v_exp_f32_e32 v1, v1
	v_sub_f32_e32 v2, v50, v151
	v_exp_f32_e32 v2, v2
	v_sub_f32_e32 v3, v51, v151
	v_exp_f32_e32 v3, v3
	v_add_f32_e32 v4, 0, v0
	v_add_f32_e32 v4, v1, v4
	v_add_f32_e32 v4, v2, v4
	v_add_f32_e32 v8, v3, v4
	v_sub_f32_e32 v4, v52, v151
	v_exp_f32_e32 v4, v4
	v_sub_f32_e32 v5, v53, v151
	v_exp_f32_e32 v5, v5
	v_sub_f32_e32 v6, v54, v151
	v_exp_f32_e32 v6, v6
	v_sub_f32_e32 v7, v55, v151
	v_exp_f32_e32 v7, v7
	v_sub_f32_e32 v9, v56, v151
	v_add_f32_e32 v8, v4, v8
	v_exp_f32_e32 v126, v9
	v_sub_f32_e32 v9, v57, v151
	v_add_f32_e32 v8, v5, v8
	v_exp_f32_e32 v127, v9
	v_sub_f32_e32 v9, v58, v151
	v_add_f32_e32 v8, v6, v8
	v_exp_f32_e32 v98, v9
	v_sub_f32_e32 v9, v59, v151
	v_add_f32_e32 v8, v7, v8
	v_exp_f32_e32 v99, v9
	v_add_f32_e32 v8, v126, v8
	v_add_f32_e32 v8, v127, v8
	v_add_f32_e32 v8, v98, v8
	v_add_f32_e32 v48, v99, v8
	v_sub_f32_e32 v8, v60, v151
	v_exp_f32_e32 v122, v8
	v_sub_f32_e32 v8, v61, v151
	v_exp_f32_e32 v123, v8
	v_sub_f32_e32 v8, v62, v151
	v_exp_f32_e32 v8, v8
	v_sub_f32_e32 v9, v63, v151
	v_exp_f32_e32 v9, v9
	v_sub_f32_e32 v32, v32, v151
	v_add_f32_e32 v48, v122, v48
	v_exp_f32_e32 v106, v32
	v_sub_f32_e32 v32, v33, v151
	v_add_f32_e32 v48, v123, v48
	v_exp_f32_e32 v107, v32
	v_sub_f32_e32 v32, v34, v151
	v_add_f32_e32 v48, v8, v48
	v_exp_f32_e32 v114, v32
	v_sub_f32_e32 v32, v35, v151
	v_add_f32_e32 v48, v9, v48
	v_exp_f32_e32 v115, v32
	v_sub_f32_e32 v33, v36, v151
	v_add_f32_e32 v32, v106, v48
	v_exp_f32_e32 v120, v33
	v_sub_f32_e32 v33, v37, v151
	v_add_f32_e32 v32, v107, v32
	v_exp_f32_e32 v121, v33
	v_sub_f32_e32 v33, v38, v151
	v_add_f32_e32 v32, v114, v32
	v_exp_f32_e32 v128, v33
	v_sub_f32_e32 v33, v39, v151
	v_add_f32_e32 v32, v115, v32
	v_exp_f32_e32 v129, v33
	v_sub_f32_e32 v33, v40, v151
	v_add_f32_e32 v32, v120, v32
	v_exp_f32_e32 v104, v33
	v_sub_f32_e32 v33, v41, v151
	v_add_f32_e32 v32, v121, v32
	v_exp_f32_e32 v105, v33
	v_sub_f32_e32 v33, v42, v151
	v_add_f32_e32 v32, v128, v32
	v_exp_f32_e32 v110, v33
	v_sub_f32_e32 v33, v43, v151
	v_add_f32_e32 v32, v129, v32
	v_exp_f32_e32 v111, v33
	v_sub_f32_e32 v33, v44, v151
	v_add_f32_e32 v32, v104, v32
	v_exp_f32_e32 v118, v33
	v_sub_f32_e32 v33, v45, v151
	v_add_f32_e32 v32, v105, v32
	v_exp_f32_e32 v119, v33
	v_sub_f32_e32 v33, v46, v151
	v_add_f32_e32 v32, v110, v32
	v_exp_f32_e32 v124, v33
	v_sub_f32_e32 v33, v47, v151
	v_add_f32_e32 v32, v111, v32
	v_exp_f32_e32 v125, v33
	v_sub_f32_e32 v16, v16, v151
	v_add_f32_e32 v32, v118, v32
	v_exp_f32_e32 v52, v16
	v_sub_f32_e32 v16, v17, v151
	v_add_f32_e32 v32, v119, v32
	v_exp_f32_e32 v53, v16
	v_sub_f32_e32 v16, v18, v151
	v_add_f32_e32 v32, v124, v32
	v_exp_f32_e32 v60, v16
	v_sub_f32_e32 v16, v19, v151
	v_add_f32_e32 v32, v125, v32
	v_exp_f32_e32 v61, v16
	v_sub_f32_e32 v17, v20, v151
	v_add_f32_e32 v16, v52, v32
	v_exp_f32_e32 v100, v17
	v_sub_f32_e32 v17, v21, v151
	v_add_f32_e32 v16, v53, v16
	v_exp_f32_e32 v101, v17
	v_sub_f32_e32 v17, v22, v151
	v_add_f32_e32 v16, v60, v16
	v_exp_f32_e32 v108, v17
	v_sub_f32_e32 v17, v23, v151
	v_add_f32_e32 v16, v61, v16
	v_exp_f32_e32 v109, v17
	v_sub_f32_e32 v17, v24, v151
	v_add_f32_e32 v16, v100, v16
	v_exp_f32_e32 v48, v17
	v_sub_f32_e32 v17, v25, v151
	v_add_f32_e32 v16, v101, v16
	v_exp_f32_e32 v49, v17
	v_sub_f32_e32 v17, v26, v151
	v_add_f32_e32 v16, v108, v16
	v_exp_f32_e32 v56, v17
	v_sub_f32_e32 v17, v27, v151
	v_add_f32_e32 v16, v109, v16
	v_exp_f32_e32 v57, v17
	v_sub_f32_e32 v17, v28, v151
	v_add_f32_e32 v16, v48, v16
	v_exp_f32_e32 v92, v17
	v_sub_f32_e32 v17, v29, v151
	v_add_f32_e32 v16, v49, v16
	v_exp_f32_e32 v93, v17
	v_sub_f32_e32 v17, v30, v151
	v_add_f32_e32 v16, v56, v16
	v_exp_f32_e32 v102, v17
	v_sub_f32_e32 v17, v31, v151
	v_add_f32_e32 v16, v57, v16
	v_exp_f32_e32 v103, v17
	v_sub_f32_e32 v17, v113, v151
	v_add_f32_e32 v16, v92, v16
	v_exp_f32_e32 v34, v17
	v_sub_f32_e32 v17, v116, v151
	v_add_f32_e32 v16, v93, v16
	v_exp_f32_e32 v35, v17
	v_sub_f32_e32 v17, v117, v151
	v_add_f32_e32 v16, v102, v16
	v_exp_f32_e32 v38, v17
	v_sub_f32_e32 v17, v130, v151
	v_add_f32_e32 v16, v103, v16
	v_exp_f32_e32 v39, v17
	v_sub_f32_e32 v17, v131, v151
	v_add_f32_e32 v16, v34, v16
	v_exp_f32_e32 v42, v17
	v_sub_f32_e32 v17, v145, v151
	v_add_f32_e32 v16, v35, v16
	v_exp_f32_e32 v43, v17
	v_sub_f32_e32 v17, v147, v151
	v_add_f32_e32 v16, v38, v16
	v_exp_f32_e32 v54, v17
	v_sub_f32_e32 v17, v148, v151
	v_add_f32_e32 v16, v39, v16
	v_exp_f32_e32 v55, v17
	v_sub_f32_e32 v17, v149, v151
	v_add_f32_e32 v16, v42, v16
	v_exp_f32_e32 v32, v17
	v_sub_f32_e32 v17, v150, v151
	v_add_f32_e32 v16, v43, v16
	v_exp_f32_e32 v33, v17
	v_sub_f32_e32 v10, v10, v151
	v_add_f32_e32 v16, v54, v16
	v_exp_f32_e32 v36, v10
	v_sub_f32_e32 v10, v11, v151
	v_add_f32_e32 v16, v55, v16
	v_exp_f32_e32 v37, v10
	v_sub_f32_e32 v11, v12, v151
	v_add_f32_e32 v10, v32, v16
	v_exp_f32_e32 v40, v11
	v_sub_f32_e32 v11, v13, v151
	v_add_f32_e32 v10, v33, v10
	v_exp_f32_e32 v41, v11
	v_sub_f32_e32 v11, v14, v151
	v_add_f32_e32 v10, v36, v10
	v_exp_f32_e32 v44, v11
	v_sub_f32_e32 v11, v15, v151
	v_add_f32_e32 v10, v37, v10
	v_exp_f32_e32 v45, v11
	v_add_f32_e32 v10, v40, v10
	v_add_f32_e32 v10, v41, v10
	v_add_f32_e32 v10, v44, v10
	v_add_f32_e32 v10, v45, v10
	v_mov_b32_e32 v11, v10
	v_mad_u32_u24 v59, v89, s4, v112
	s_waitcnt lgkmcnt(0)
; DI f32x16 mma32(bf16x8 a, bf16x8 b, f32x16 c) { return __builtin_amdgcn_mfma_f32_32x32x16_bf16(a, b, c, 0, 0, 0); }
; DI bf16x8 packp(const f32x16& x, const int h8) { v4u p; p.x = pk2(x[h8 + 0], x[h8 + 1]); p.y = pk2(x[h8 + 2], x[h8 + 3]); p.z = pk2(x[h8 + 4], x[h8 + 5]); p.w = pk2(x[h8 + 6], x[h8 + 7]); return __builtin_bit_cast(bf16x8, p); }
; DI void nsa_item(KA a, LAS unsigned char* lds, const int it) {
;     ...
;         ls += __shfl_xor(ls, 32); const float inv = ls > 0.f ? 1.f / ls : 0.f;
; #pragma unroll
;         for (int k4 = 0; k4 < 4; ++k4) st[k4] = st[k4] * inv;
;         f32x16 ot[2] = {ZERO16, ZERO16};
; #pragma unroll
;         for (int sp = 0; sp < 8; ++sp) { const bf16x8 pf = packp(st[sp >> 1], 8 * (sp & 1));
; #pragma unroll
;             for (int dh = 0; dh < 2; ++dh) ot[dh] = mma32(vfrag(VT, 32 * dh + r, sp, hf), pf, ot[dh]); }
;         of[0] = ot[0] * g0; of[1] = ot[1] * g0;
;         if (qb >= 16) {
	s_nop 1
	v_permlane32_swap_b32_e32 v11, v10
	v_add_f32_e32 v10, v10, v11
	v_div_scale_f32 v11, s[0:1], v10, v10, 1.0
	v_rcp_f32_e32 v12, v11
	s_mov_b64 s[0:1], -1
	v_fma_f32 v13, -v11, v12, 1.0
	v_fmac_f32_e32 v12, v13, v12
	v_div_scale_f32 v13, vcc, 1.0, v10, 1.0
	v_mul_f32_e32 v14, v13, v12
	v_fma_f32 v15, -v11, v14, v13
	v_fmac_f32_e32 v14, v15, v12
	v_fma_f32 v11, -v11, v14, v13
	v_div_fmas_f32 v11, v11, v12, v14
	v_div_fixup_f32 v11, v11, v10, 1.0
	v_cmp_lt_f32_e32 vcc, 0, v10
	s_nop 1
	v_cndmask_b32_e32 v58, 0, v11, vcc
	ds_read_b128 v[10:13], v59 offset:18432
	v_pk_mul_f32 v[46:47], v[6:7], v[58:59] op_sel_hi:[1,0]
	v_pk_mul_f32 v[112:113], v[4:5], v[58:59] op_sel_hi:[1,0]
	v_pk_mul_f32 v[50:51], v[2:3], v[58:59] op_sel_hi:[1,0]
	v_pk_mul_f32 v[116:117], v[0:1], v[58:59] op_sel_hi:[1,0]
	v_cvt_pk_bf16_f32 v1, v50, v51
	v_cvt_pk_bf16_f32 v0, v116, v117
	v_cvt_pk_bf16_f32 v2, v112, v113
	v_cvt_pk_bf16_f32 v3, v46, v47
	ds_read_b128 v[4:7], v59 offset:27136
	ds_read_b128 v[148:151], v59 offset:18464
	s_waitcnt lgkmcnt(2)
	v_mfma_f32_32x32x16_bf16 v[16:31], v[10:13], v[0:3], 0
	v_mul_f32_e64 v62, v8, v58
	v_mul_f32_e64 v63, v9, v58
	v_mul_f32_e64 v122, v122, v58
	v_mul_f32_e64 v123, v123, v58
	v_mul_f32_e64 v98, v98, v58
	v_mul_f32_e64 v99, v99, v58
	v_pk_mul_f32 v[126:127], v[126:127], v[58:59] op_sel_hi:[1,0]
	v_cvt_pk_bf16_f32 v153, v98, v99
	v_cvt_pk_bf16_f32 v152, v126, v127
	v_cvt_pk_bf16_f32 v154, v122, v123
	v_cvt_pk_bf16_f32 v155, v62, v63
	s_waitcnt lgkmcnt(1)
	v_mfma_f32_32x32x16_bf16 v[0:15], v[4:7], v[0:3], 0
	ds_read_b128 v[156:159], v59 offset:18496
	v_mul_f32_e64 v128, v128, v58
	v_mul_f32_e64 v129, v129, v58
	v_mul_f32_e64 v120, v120, v58
	v_mul_f32_e64 v121, v121, v58
	v_pk_mul_f32 v[114:115], v[114:115], v[58:59] op_sel_hi:[1,0]
	v_pk_mul_f32 v[130:131], v[106:107], v[58:59] op_sel_hi:[1,0]
	v_pk_mul_f32 v[106:107], v[124:125], v[58:59] op_sel_hi:[1,0]
	v_pk_mul_f32 v[118:119], v[118:119], v[58:59] op_sel_hi:[1,0]
	s_waitcnt lgkmcnt(1)
	v_mfma_f32_32x32x16_bf16 v[16:31], v[148:151], v[152:155], v[16:31]
	ds_read_b128 v[148:151], v59 offset:27168
	v_mul_f32_e64 v110, v110, v58
	v_mul_f32_e64 v111, v111, v58
	v_mul_f32_e64 v104, v104, v58
	v_mul_f32_e64 v105, v105, v58
	v_pk_mul_f32 v[108:109], v[108:109], v[58:59] op_sel_hi:[1,0]
	v_pk_mul_f32 v[100:101], v[100:101], v[58:59] op_sel_hi:[1,0]
	v_pk_mul_f32 v[60:61], v[60:61], v[58:59] op_sel_hi:[1,0]
	v_pk_mul_f32 v[124:125], v[52:53], v[58:59] op_sel_hi:[1,0]
	s_waitcnt lgkmcnt(0)
	v_mfma_f32_32x32x16_bf16 v[0:15], v[148:151], v[152:155], v[0:15]
	v_cvt_pk_bf16_f32 v148, v130, v131
	v_cvt_pk_bf16_f32 v149, v114, v115
	v_cvt_pk_bf16_f32 v150, v120, v121
	v_cvt_pk_bf16_f32 v151, v128, v129
	v_mul_f32_e64 v52, v102, v58
	v_mul_f32_e64 v53, v103, v58
	v_pk_mul_f32 v[102:103], v[92:93], v[58:59] op_sel_hi:[1,0]
	v_pk_mul_f32 v[56:57], v[56:57], v[58:59] op_sel_hi:[1,0]
	v_mfma_f32_32x32x16_bf16 v[16:31], v[156:159], v[148:151], v[16:31]
	ds_read_b128 v[152:155], v59 offset:27200
	ds_read_b128 v[156:159], v59 offset:18528
	v_mul_f32_e64 v48, v48, v58
	v_mul_f32_e64 v49, v49, v58
	v_mul_f32_e64 v54, v54, v58
	v_mul_f32_e64 v55, v55, v58
	v_pk_mul_f32 v[42:43], v[42:43], v[58:59] op_sel_hi:[1,0]
	v_pk_mul_f32 v[38:39], v[38:39], v[58:59] op_sel_hi:[1,0]
	v_pk_mul_f32 v[34:35], v[34:35], v[58:59] op_sel_hi:[1,0]
	v_pk_mul_f32 v[44:45], v[44:45], v[58:59] op_sel_hi:[1,0]
	s_waitcnt lgkmcnt(1)
	v_mfma_f32_32x32x16_bf16 v[0:15], v[152:155], v[148:151], v[0:15]
	ds_read_b128 v[152:155], v59 offset:27232
	v_cvt_pk_bf16_f32 v148, v104, v105
	v_cvt_pk_bf16_f32 v149, v110, v111
	v_cvt_pk_bf16_f32 v150, v118, v119
	v_cvt_pk_bf16_f32 v151, v106, v107
	v_pk_mul_f32 v[40:41], v[40:41], v[58:59] op_sel_hi:[1,0]
	v_pk_mul_f32 v[36:37], v[36:37], v[58:59] op_sel_hi:[1,0]
	s_waitcnt lgkmcnt(1)
	v_mfma_f32_32x32x16_bf16 v[16:31], v[156:159], v[148:151], v[16:31]
	ds_read_b128 v[156:159], v59 offset:18560
	v_mul_f32_e64 v32, v32, v58
	v_mul_f32_e64 v33, v33, v58
	v_lshlrev_b32_e32 v58, 2, v141
	s_waitcnt lgkmcnt(1)
	v_mfma_f32_32x32x16_bf16 v[0:15], v[152:155], v[148:151], v[0:15]
	v_cvt_pk_bf16_f32 v148, v124, v125
	v_cvt_pk_bf16_f32 v149, v60, v61
	v_cvt_pk_bf16_f32 v150, v100, v101
	v_cvt_pk_bf16_f32 v151, v108, v109
	s_waitcnt lgkmcnt(0)
	s_nop 0
	v_mfma_f32_32x32x16_bf16 v[16:31], v[156:159], v[148:151], v[16:31]
	ds_read_b128 v[152:155], v59 offset:27264
	ds_read_b128 v[156:159], v59 offset:18592
	s_waitcnt lgkmcnt(1)
	v_mfma_f32_32x32x16_bf16 v[0:15], v[152:155], v[148:151], v[0:15]
	ds_read_b128 v[152:155], v59 offset:27296
	v_cvt_pk_bf16_f32 v148, v48, v49
	v_cvt_pk_bf16_f32 v149, v56, v57
	v_cvt_pk_bf16_f32 v150, v102, v103
	v_cvt_pk_bf16_f32 v151, v52, v53
	s_waitcnt lgkmcnt(1)
	s_nop 0
	v_mfma_f32_32x32x16_bf16 v[16:31], v[156:159], v[148:151], v[16:31]
	ds_read_b128 v[156:159], v59 offset:18624
	s_waitcnt lgkmcnt(1)
	v_mfma_f32_32x32x16_bf16 v[0:15], v[152:155], v[148:151], v[0:15]
	v_cvt_pk_bf16_f32 v148, v34, v35
	v_cvt_pk_bf16_f32 v149, v38, v39
	v_cvt_pk_bf16_f32 v150, v42, v43
	v_cvt_pk_bf16_f32 v151, v54, v55
	s_waitcnt lgkmcnt(0)
	s_nop 0
	v_mfma_f32_32x32x16_bf16 v[16:31], v[156:159], v[148:151], v[16:31]
	ds_read_b128 v[152:155], v59 offset:27328
	ds_read_b128 v[156:159], v59 offset:18656
	s_waitcnt lgkmcnt(1)
	v_mfma_f32_32x32x16_bf16 v[0:15], v[152:155], v[148:151], v[0:15]
	ds_read_b128 v[152:155], v59 offset:27360
	v_cvt_pk_bf16_f32 v148, v32, v33
	v_cvt_pk_bf16_f32 v149, v36, v37
	v_cvt_pk_bf16_f32 v150, v40, v41
	v_cvt_pk_bf16_f32 v151, v44, v45
	s_waitcnt lgkmcnt(1)
	s_nop 0
	v_mfma_f32_32x32x16_bf16 v[16:31], v[156:159], v[148:151], v[16:31]
	s_waitcnt lgkmcnt(0)
	v_mfma_f32_32x32x16_bf16 v[0:15], v[152:155], v[148:151], v[0:15]
	s_cbranch_scc0 .LBB0_610
	v_lshlrev_b32_e32 v145, 2, v141
	s_mov_b64 s[0:1], 0
